# attention: K and V^T staged in two steps (V^T loads overlap QK^T+softmax, second barrier before P.V)
# baseline (speedup 1.0000x reference)
; #define LAS __attribute__((address_space(3)))
; __device__ __forceinline__ void attn_phase(const Params& p, LAS unsigned char* lds) {
;     ...
;         const int b = item >> 7, h = (item >> 4) & 7, r0 = (item & 15) * 2, R0 = min(max(r0 - 4, 0), 24);
;         const int r = r0 + ri, rs = min(max(r - 4, 0), 24), j0 = rs - R0;
;         const int tq = b * SEQ + r * 64 + q0 + fr;
;         const bf16_t* qp = QH + ((size_t)(b * 8 + h) * SEQ + r * 64 + q0 + fr) * 64 + fq * 8;
;         const bf16x8 qf0 = *(const bf16x8*)qp, qf1 = *(const bf16x8*)(qp + 32);
;         for (int u = tid; u < 465; u += NTHREADS) rp[u] = p.rpb[h * 465 + u] * 1.4426950408889634f;
;         { const int t = tid >> 3, c = tid & 7; const unsigned dstk = (unsigned)(t * 128 + ((c ^ (((t >> 1) & 1) | (((t >> 3) & 3) << 1))) << 4)), dstv = (unsigned)(t * 128 + ((c ^ ((t >> 1) & 7)) << 4));
;           u32x4 kv[9], vv[9];
; #pragma unroll
;           for (int j = 0; j < 9; ++j) { const int srow = min(R0 + j, 31);
;               kv[j] = *(const u32x4*)(KH + ((size_t)(b * 8 + h) * SEQ + srow * 64 + t) * 64 + c * 8);
;               vv[j] = *(const u32x4*)(VTA + ((size_t)((b * 8 + h) * 32 + srow) * 64 + t) * 64 + c * 8); }
; #pragma unroll
;           for (int j = 0; j < 9; ++j) { *(LAS u32x4*)(Ks + j * 8192 + dstk) = kv[j]; *(LAS u32x4*)(Vs + j * 8192 + dstv) = vv[j]; } }
.LBB0_345:
	s_or_b64 exec, exec, s[38:39]
	v_sub_u32_e64 v0, s16, 4 clamp
	v_or_b32_e32 v108, s26, v128
	v_readfirstlane_b32 s38, v0
	s_min_u32 s39, s38, 24
	s_lshl_b32 s26, s20, 5
	s_or_b32 s20, s39, s26
	s_ashr_i32 s21, s20, 31
	s_lshl_b64 s[20:21], s[20:21], 13
	v_lshl_add_u64 v[8:9], v[36:37], 0, s[20:21]
	s_or_b32 s20, s39, 1
	s_lshl_b32 s16, s20, 6
	s_or_b32 s20, s20, s26
	s_ashr_i32 s21, s20, 31
	s_lshl_b64 s[20:21], s[20:21], 13
	v_mov_b32_e32 v109, s27
	v_lshl_add_u64 v[20:21], v[36:37], 0, s[20:21]
	s_add_i32 s20, s39, 2
	v_lshl_add_u64 v[16:17], v[108:109], 0, s[16:17]
	s_lshl_b32 s16, s20, 6
	s_or_b32 s20, s20, s26
	s_ashr_i32 s21, s20, 31
	s_lshl_b64 s[20:21], s[20:21], 13
	v_lshl_add_u64 v[64:65], v[36:37], 0, s[20:21]
	s_add_i32 s20, s39, 3
	v_lshl_add_u64 v[24:25], v[108:109], 0, s[16:17]
	s_lshl_b32 s16, s20, 6
	s_or_b32 s20, s20, s26
	s_ashr_i32 s21, s20, 31
	s_lshl_b64 s[20:21], s[20:21], 13
	v_lshl_add_u64 v[72:73], v[36:37], 0, s[20:21]
	s_add_i32 s20, s39, 4
	v_lshl_add_u64 v[68:69], v[108:109], 0, s[16:17]
	s_lshl_b32 s16, s20, 6
	s_or_b32 s20, s20, s26
	s_ashr_i32 s21, s20, 31
	s_lshl_b64 s[20:21], s[20:21], 13
	v_lshl_add_u64 v[80:81], v[36:37], 0, s[20:21]
	s_add_i32 s20, s39, 5
	v_lshl_add_u64 v[76:77], v[108:109], 0, s[16:17]
	s_lshl_b32 s16, s20, 6
	s_or_b32 s20, s20, s26
	s_ashr_i32 s21, s20, 31
	s_lshl_b64 s[20:21], s[20:21], 13
	v_lshl_add_u64 v[88:89], v[36:37], 0, s[20:21]
	s_add_i32 s20, s39, 6
	v_lshl_add_u64 v[84:85], v[108:109], 0, s[16:17]
	s_lshl_b32 s16, s20, 6
	s_or_b32 s20, s20, s26
	s_ashr_i32 s21, s20, 31
	s_lshl_b64 s[20:21], s[20:21], 13
	v_lshl_add_u64 v[96:97], v[36:37], 0, s[20:21]
	s_add_i32 s20, s39, 7
	v_lshl_add_u64 v[92:93], v[108:109], 0, s[16:17]
	s_lshl_b32 s16, s20, 6
	s_or_b32 s20, s20, s26
	s_ashr_i32 s21, s20, 31
	v_lshl_add_u64 v[100:101], v[108:109], 0, s[16:17]
	s_lshl_b64 s[20:21], s[20:21], 13
	s_min_u32 s16, s38, 23
	v_lshl_add_u64 v[104:105], v[36:37], 0, s[20:21]
	s_add_i32 s20, s16, 8
	s_lshl_b32 s16, s20, 6
	s_or_b32 s20, s20, s26
	v_lshl_or_b32 v0, s39, 6, v108
	v_mov_b32_e32 v1, s27
	v_lshl_add_u64 v[108:109], v[108:109], 0, s[16:17]
	s_ashr_i32 s21, s20, 31
	v_lshlrev_b64 v[0:1], 7, v[0:1]
	v_lshlrev_b64 v[16:17], 7, v[16:17]
	v_lshlrev_b64 v[24:25], 7, v[24:25]
	v_lshlrev_b64 v[68:69], 7, v[68:69]
	v_lshlrev_b64 v[76:77], 7, v[76:77]
	v_lshlrev_b64 v[84:85], 7, v[84:85]
	v_lshlrev_b64 v[92:93], 7, v[92:93]
	v_lshlrev_b64 v[100:101], 7, v[100:101]
	v_lshlrev_b64 v[108:109], 7, v[108:109]
	s_lshl_b64 s[20:21], s[20:21], 13
	v_lshl_add_u64 v[0:1], v[34:35], 0, v[0:1]
	v_lshl_add_u64 v[16:17], v[34:35], 0, v[16:17]
	v_lshl_add_u64 v[24:25], v[34:35], 0, v[24:25]
	v_lshl_add_u64 v[68:69], v[34:35], 0, v[68:69]
	v_lshl_add_u64 v[76:77], v[34:35], 0, v[76:77]
	v_lshl_add_u64 v[84:85], v[34:35], 0, v[84:85]
	v_lshl_add_u64 v[92:93], v[34:35], 0, v[92:93]
	v_lshl_add_u64 v[100:101], v[34:35], 0, v[100:101]
	v_lshl_add_u64 v[108:109], v[34:35], 0, v[108:109]
	v_lshl_add_u64 v[112:113], v[36:37], 0, s[20:21]
	global_load_dwordx4 v[0:3], v[0:1], off
	s_nop 0
	global_load_dwordx4 v[16:19], v[16:17], off
	s_nop 0
	global_load_dwordx4 v[24:27], v[24:25], off
	s_nop 0
	global_load_dwordx4 v[68:71], v[68:69], off
	s_nop 0
	global_load_dwordx4 v[76:79], v[76:77], off
	s_nop 0
	global_load_dwordx4 v[84:87], v[84:85], off
	s_nop 0
	global_load_dwordx4 v[92:95], v[92:93], off
	s_nop 0
	global_load_dwordx4 v[100:103], v[100:101], off
	s_nop 0
	global_load_dwordx4 v[108:111], v[108:109], off
	s_nop 0
	global_load_dwordx4 v[176:179], v[8:9], off
	s_nop 0
	global_load_dwordx4 v[180:183], v[20:21], off
	s_nop 0
	global_load_dwordx4 v[184:187], v[64:65], off
	s_nop 0
	global_load_dwordx4 v[188:191], v[72:73], off
	s_nop 0
	global_load_dwordx4 v[192:195], v[80:81], off
	s_nop 0
	global_load_dwordx4 v[196:199], v[88:89], off
	s_nop 0
	global_load_dwordx4 v[200:203], v[96:97], off
	s_nop 0
	global_load_dwordx4 v[204:207], v[104:105], off
	s_nop 0
	global_load_dwordx4 v[208:211], v[112:113], off
	s_max_i32 s16, s45, 4
	s_add_i32 s16, s16, -4
	s_min_u32 s20, s16, 24
	s_sub_i32 s16, s20, s39
	s_lshl_b32 s16, s16, 13
	s_sub_i32 s20, s20, s45
	s_mulk_i32 s20, 0x7c
	s_add_i32 s20, s20, 0
	s_add_i32 s20, s20, 0x24000
	v_lshl_add_u32 v118, v58, 2, s20
	v_lshl_add_u32 v119, v60, 2, s20
	s_waitcnt vmcnt(18)
	s_and_saveexec_b64 s[98:99], s[0:1]
	v_mul_f32_e32 v241, 0x3fb8aa3b, v241
	ds_write_b32 v42, v241
	s_or_b64 exec, exec, s[98:99]
	s_waitcnt vmcnt(17)
	ds_write_b128 v29, v[0:3]
	s_waitcnt vmcnt(16)
	ds_write_b128 v29, v[16:19] offset:8192
	s_waitcnt vmcnt(15)
	ds_write_b128 v29, v[24:27] offset:16384
	s_waitcnt vmcnt(14)
	ds_write_b128 v29, v[68:71] offset:24576
	s_waitcnt vmcnt(13)
	ds_write_b128 v29, v[76:79] offset:32768
	s_waitcnt vmcnt(12)
	ds_write_b128 v29, v[84:87] offset:40960
	s_waitcnt vmcnt(11)
	ds_write_b128 v29, v[92:95] offset:49152
	s_waitcnt vmcnt(10)
	ds_write_b128 v29, v[100:103] offset:57344
	s_waitcnt vmcnt(9)
	ds_write_b128 v43, v[108:111]
	v_add_u32_e32 v8, s16, v61
	v_add_u32_e32 v63, v8, v39
	s_waitcnt lgkmcnt(0)
	s_barrier
; #define LAS __attribute__((address_space(3)))
; __device__ __forceinline__ void attn_phase(const Params& p, LAS unsigned char* lds) {
;     ...
;         f32x4 s[8][2];
; #pragma unroll
;         for (int i = 0; i < 8; ++i)
; #pragma unroll
;             for (int t = 0; t < 2; ++t) { const int tok = kc0 + kperm + 4 * t; const LAS unsigned char* kr = Ks + (j0 + i) * 8192 + tok * 128;
;                 const int fk = ((tok >> 1) & 1) | (((tok >> 3) & 3) << 1);
;                 const bf16x8 k0 = *(const LAS bf16x8*)(kr + ((fq ^ fk) << 4)), k1 = *(const LAS bf16x8*)(kr + (((4 + fq) ^ fk) << 4));
;                 f32x4 a = (f32x4){0.f, 0.f, 0.f, 0.f};
;                 a = __builtin_amdgcn_mfma_f32_16x16x32_bf16(k0, qf0, a, 0, 0, 0); a = __builtin_amdgcn_mfma_f32_16x16x32_bf16(k1, qf1, a, 0, 0, 0); s[i][t] = a; }
;         const int qc = q0 + fr, cs0 = min(max(qc - 8, 0), 48);
;         float madd[2][4]; int dco[2][4];
; #pragma unroll
;         for (int t = 0; t < 2; ++t)
; #pragma unroll
;             for (int j = 0; j < 4; ++j) { const int kc = kc0 + 8 * fq + 4 * t + j; madd[t][j] = ((kc >= cs0) && (kc < cs0 + 16)) ? 0.f : -1e30f; dco[t][j] = min(max(kc - qc, -15), 15); }
;         float mx = -1e30f;
; #pragma unroll
;         for (int i = 0; i < 8; ++i) { const int dr = rs + i - r; const LAS float* rrow = rp + (dr + 7) * 31 + 15;
; #pragma unroll
;             for (int t = 0; t < 2; ++t)
; #pragma unroll
;                 for (int j = 0; j < 4; ++j) { const float v = (s[i][t][j] * sc2 + rrow[dco[t][j]]) + madd[t][j]; s[i][t][j] = v; mx = fmaxf(mx, v); } }
	ds_read_b128 v[0:3], v63
	v_add_u32_e32 v112, v8, v40
	ds_read_b128 v[8:11], v63 offset:512
	s_waitcnt lgkmcnt(1)
	v_mfma_f32_16x16x32_bf16 v[0:3], v[0:3], v[12:15], 0
	ds_read_b128 v[16:19], v112
	ds_read_b128 v[20:23], v112 offset:512
	s_waitcnt lgkmcnt(1)
	v_mfma_f32_16x16x32_bf16 v[64:67], v[16:19], v[4:7], v[0:3]
	v_mfma_f32_16x16x32_bf16 v[0:3], v[8:11], v[12:15], 0
	s_waitcnt lgkmcnt(0)
	v_mfma_f32_16x16x32_bf16 v[68:71], v[20:23], v[4:7], v[0:3]
	s_nop 5
	ds_read_b128 v[0:3], v63 offset:8192
	ds_read_b128 v[8:11], v63 offset:8704
	ds_read_b128 v[16:19], v112 offset:8192
	ds_read_b128 v[20:23], v112 offset:8704
	s_waitcnt lgkmcnt(3)
	v_mfma_f32_16x16x32_bf16 v[0:3], v[0:3], v[12:15], 0
	s_waitcnt lgkmcnt(1)
	v_mfma_f32_16x16x32_bf16 v[72:75], v[16:19], v[4:7], v[0:3]
	v_mfma_f32_16x16x32_bf16 v[0:3], v[8:11], v[12:15], 0
	s_waitcnt lgkmcnt(0)
	v_mfma_f32_16x16x32_bf16 v[76:79], v[20:23], v[4:7], v[0:3]
	s_nop 5
	ds_read_b128 v[0:3], v63 offset:16384
	ds_read_b128 v[8:11], v63 offset:16896
	ds_read_b128 v[16:19], v112 offset:16384
	ds_read_b128 v[20:23], v112 offset:16896
	s_waitcnt lgkmcnt(3)
	v_mfma_f32_16x16x32_bf16 v[0:3], v[0:3], v[12:15], 0
	s_waitcnt lgkmcnt(1)
	v_mfma_f32_16x16x32_bf16 v[80:83], v[16:19], v[4:7], v[0:3]
	v_mfma_f32_16x16x32_bf16 v[0:3], v[8:11], v[12:15], 0
	s_waitcnt lgkmcnt(0)
	v_mfma_f32_16x16x32_bf16 v[84:87], v[20:23], v[4:7], v[0:3]
	s_nop 5
	ds_read_b128 v[0:3], v63 offset:24576
	ds_read_b128 v[8:11], v63 offset:25088
	ds_read_b128 v[16:19], v112 offset:24576
	ds_read_b128 v[20:23], v112 offset:25088
	s_waitcnt lgkmcnt(3)
	v_mfma_f32_16x16x32_bf16 v[0:3], v[0:3], v[12:15], 0
	s_waitcnt lgkmcnt(1)
	v_mfma_f32_16x16x32_bf16 v[88:91], v[16:19], v[4:7], v[0:3]
	v_mfma_f32_16x16x32_bf16 v[0:3], v[8:11], v[12:15], 0
	s_waitcnt lgkmcnt(0)
	v_mfma_f32_16x16x32_bf16 v[92:95], v[20:23], v[4:7], v[0:3]
	s_nop 5
	ds_read_b128 v[0:3], v63 offset:32768
	ds_read_b128 v[8:11], v63 offset:33280
	ds_read_b128 v[16:19], v112 offset:32768
	ds_read_b128 v[20:23], v112 offset:33280
	s_waitcnt lgkmcnt(3)
	v_mfma_f32_16x16x32_bf16 v[0:3], v[0:3], v[12:15], 0
	s_waitcnt lgkmcnt(1)
	v_mfma_f32_16x16x32_bf16 v[96:99], v[16:19], v[4:7], v[0:3]
	v_mfma_f32_16x16x32_bf16 v[0:3], v[8:11], v[12:15], 0
	s_waitcnt lgkmcnt(0)
	v_mfma_f32_16x16x32_bf16 v[100:103], v[20:23], v[4:7], v[0:3]
	s_nop 5
	ds_read_b128 v[0:3], v63 offset:40960
	ds_read_b128 v[8:11], v63 offset:41472
	ds_read_b128 v[16:19], v112 offset:40960
	ds_read_b128 v[20:23], v112 offset:41472
	s_waitcnt lgkmcnt(3)
	v_mfma_f32_16x16x32_bf16 v[0:3], v[0:3], v[12:15], 0
	s_waitcnt lgkmcnt(1)
	v_mfma_f32_16x16x32_bf16 v[24:27], v[16:19], v[4:7], v[0:3]
	v_mfma_f32_16x16x32_bf16 v[0:3], v[8:11], v[12:15], 0
	s_waitcnt lgkmcnt(0)
	v_mfma_f32_16x16x32_bf16 v[20:23], v[20:23], v[4:7], v[0:3]
	s_nop 5
	ds_read_b128 v[0:3], v63 offset:49152
	ds_read_b128 v[8:11], v63 offset:49664
	ds_read_b128 v[16:19], v112 offset:49152
	ds_read_b128 v[104:107], v112 offset:49664
	s_waitcnt lgkmcnt(3)
	v_mfma_f32_16x16x32_bf16 v[0:3], v[0:3], v[12:15], 0
	s_waitcnt lgkmcnt(1)
	v_mfma_f32_16x16x32_bf16 v[16:19], v[16:19], v[4:7], v[0:3]
	v_mfma_f32_16x16x32_bf16 v[0:3], v[8:11], v[12:15], 0
	s_waitcnt lgkmcnt(0)
	v_mfma_f32_16x16x32_bf16 v[8:11], v[104:107], v[4:7], v[0:3]
	s_nop 5
	ds_read_b128 v[0:3], v63 offset:57344
	ds_read_b128 v[104:107], v63 offset:57856
	ds_read_b128 v[108:111], v112 offset:57344
	ds_read_b128 v[112:115], v112 offset:57856
	v_lshl_add_u32 v63, v46, 2, s20
	s_waitcnt lgkmcnt(3)
	v_mfma_f32_16x16x32_bf16 v[0:3], v[0:3], v[12:15], 0
	s_waitcnt lgkmcnt(1)
	v_mfma_f32_16x16x32_bf16 v[0:3], v[108:111], v[4:7], v[0:3]
	v_lshl_add_u32 v110, v48, 2, s20
	v_lshl_add_u32 v111, v52, 2, s20
	v_mfma_f32_16x16x32_bf16 v[12:15], v[104:107], v[12:15], 0
	v_add_u32_e32 v104, 0x200, v63
	v_add_u32_e32 v106, 0x200, v110
	ds_read2_b32 v[104:105], v104 offset0:104 offset1:135
	ds_read2_b32 v[106:107], v106 offset0:104 offset1:135
	s_waitcnt lgkmcnt(2)
	v_mfma_f32_16x16x32_bf16 v[4:7], v[112:115], v[4:7], v[12:15]
	v_lshl_add_u32 v114, v54, 2, s20
	v_lshl_add_u32 v115, v56, 2, s20
	s_waitcnt lgkmcnt(1)
	v_fmac_f32_e32 v105, 0x3e38aa3b, v72
	v_fmamk_f32 v12, v64, 0x3e38aa3b, v104
	s_waitcnt lgkmcnt(0)
	v_fmamk_f32 v64, v65, 0x3e38aa3b, v106
	v_lshl_add_u32 v106, v50, 2, s20
	v_add_f32_e32 v104, v45, v12
	v_add_u32_e32 v12, 0x200, v106
	ds_read2_b32 v[12:13], v12 offset0:104 offset1:135
	v_add_u32_e32 v14, 0x200, v111
	ds_read2_b32 v[14:15], v14 offset0:104 offset1:135
	v_add_f32_e32 v112, v47, v64
	v_max3_f32 v108, v104, s11, v112
	s_waitcnt lgkmcnt(1)
	v_fmamk_f32 v12, v66, 0x3e38aa3b, v12
	v_add_f32_e32 v113, v49, v12
	s_waitcnt lgkmcnt(0)
	v_fmamk_f32 v12, v67, 0x3e38aa3b, v14
	v_add_u32_e32 v14, 0x200, v114
	ds_read2_b32 v[64:65], v14 offset0:104 offset1:135
	v_add_u32_e32 v14, 0x200, v115
	ds_read2_b32 v[66:67], v14 offset0:104 offset1:135
	v_add_f32_e32 v116, v51, v12
	v_max3_f32 v12, v108, v113, v116
	s_waitcnt lgkmcnt(1)
	v_fmamk_f32 v14, v68, 0x3e38aa3b, v64
	v_add_u32_e32 v64, 0x200, v118
	v_add_f32_e32 v117, v53, v14
	s_waitcnt lgkmcnt(0)
	v_fmamk_f32 v14, v69, 0x3e38aa3b, v66
	ds_read2_b32 v[68:69], v64 offset0:104 offset1:135
	v_add_u32_e32 v64, 0x200, v119
	ds_read2_b32 v[108:109], v64 offset0:104 offset1:135
	v_add_f32_e32 v120, v55, v14
	v_max3_f32 v12, v12, v117, v120
	s_waitcnt lgkmcnt(1)
	v_fmamk_f32 v14, v70, 0x3e38aa3b, v68
	v_add_f32_e32 v121, v57, v14
	s_waitcnt lgkmcnt(0)
; #define LAS __attribute__((address_space(3)))
; __device__ __forceinline__ void attn_phase(const Params& p, LAS unsigned char* lds) {
;     ...
;         float mx = -1e30f;
; #pragma unroll
;         for (int i = 0; i < 8; ++i) { const int dr = rs + i - r; const LAS float* rrow = rp + (dr + 7) * 31 + 15;
; #pragma unroll
;             for (int t = 0; t < 2; ++t)
; #pragma unroll
;                 for (int j = 0; j < 4; ++j) { const float v = (s[i][t][j] * sc2 + rrow[dco[t][j]]) + madd[t][j]; s[i][t][j] = v; mx = fmaxf(mx, v); } }
	v_fmamk_f32 v14, v71, 0x3e38aa3b, v108
	v_add_f32_e32 v108, v59, v14
	v_fmac_f32_e32 v107, 0x3e38aa3b, v73
	v_max3_f32 v12, v12, v121, v108
	v_add_f32_e32 v105, v45, v105
	v_add_f32_e32 v107, v47, v107
	v_fmac_f32_e32 v13, 0x3e38aa3b, v74
	v_fmac_f32_e32 v15, 0x3e38aa3b, v75
	v_max3_f32 v12, v12, v105, v107
	v_add_f32_e32 v122, v49, v13
	v_add_f32_e32 v123, v51, v15
	v_fmac_f32_e32 v65, 0x3e38aa3b, v76
	v_fmac_f32_e32 v67, 0x3e38aa3b, v77
	v_max3_f32 v12, v12, v122, v123
	v_add_f32_e32 v76, v53, v65
	v_add_f32_e32 v77, v55, v67
	v_add_u32_e32 v63, 0x400, v63
	v_max3_f32 v64, v12, v76, v77
	v_fmac_f32_e32 v109, 0x3e38aa3b, v79
	ds_read2_b32 v[12:13], v63 offset0:38 offset1:69
	v_add_u32_e32 v79, 0x400, v110
	ds_read2_b32 v[14:15], v79 offset0:38 offset1:69
	v_fmac_f32_e32 v69, 0x3e38aa3b, v78
	v_add_f32_e32 v78, v57, v69
	s_waitcnt lgkmcnt(1)
	v_fmamk_f32 v12, v80, 0x3e38aa3b, v12
	v_add_f32_e32 v109, v59, v109
	v_add_f32_e32 v80, v45, v12
	s_waitcnt lgkmcnt(0)
	v_fmamk_f32 v12, v81, 0x3e38aa3b, v14
	v_add_u32_e32 v81, 0x400, v106
	v_max3_f32 v68, v64, v78, v109
	ds_read2_b32 v[64:65], v81 offset0:38 offset1:69
	v_add_u32_e32 v106, 0x400, v111
	ds_read2_b32 v[66:67], v106 offset0:38 offset1:69
	v_add_f32_e32 v110, v47, v12
	v_max3_f32 v12, v68, v80, v110
	s_waitcnt lgkmcnt(1)
	v_fmamk_f32 v14, v82, 0x3e38aa3b, v64
	v_add_f32_e32 v82, v49, v14
	s_waitcnt lgkmcnt(0)
	v_fmamk_f32 v14, v83, 0x3e38aa3b, v66
	v_add_u32_e32 v83, 0x400, v114
	ds_read2_b32 v[68:69], v83 offset0:38 offset1:69
	v_add_u32_e32 v111, 0x400, v115
	ds_read2_b32 v[70:71], v111 offset0:38 offset1:69
	v_add_f32_e32 v114, v51, v14
	v_add_u32_e32 v115, 0x400, v119
	s_waitcnt lgkmcnt(1)
	v_fmamk_f32 v14, v84, 0x3e38aa3b, v68
	v_add_f32_e32 v84, v53, v14
	s_waitcnt lgkmcnt(0)
	v_fmamk_f32 v14, v85, 0x3e38aa3b, v70
	v_add_u32_e32 v85, 0x400, v118
	ds_read2_b32 v[72:73], v85 offset0:38 offset1:69
	ds_read2_b32 v[74:75], v115 offset0:38 offset1:69
	v_add_f32_e32 v118, v55, v14
	v_max3_f32 v12, v12, v82, v114
	v_max3_f32 v12, v12, v84, v118
	s_waitcnt lgkmcnt(1)
	v_fmamk_f32 v14, v86, 0x3e38aa3b, v72
	v_add_f32_e32 v86, v57, v14
	s_waitcnt lgkmcnt(0)
	v_fmamk_f32 v14, v87, 0x3e38aa3b, v74
	v_add_f32_e32 v87, v59, v14
	v_fmac_f32_e32 v13, 0x3e38aa3b, v88
	v_fmac_f32_e32 v15, 0x3e38aa3b, v89
	v_max3_f32 v12, v12, v86, v87
	v_add_f32_e32 v88, v45, v13
	v_add_f32_e32 v89, v47, v15
	v_fmac_f32_e32 v65, 0x3e38aa3b, v90
	v_fmac_f32_e32 v67, 0x3e38aa3b, v91
	v_max3_f32 v12, v12, v88, v89
	v_add_f32_e32 v90, v49, v65
	v_add_f32_e32 v91, v51, v67
	v_fmac_f32_e32 v69, 0x3e38aa3b, v92
	v_fmac_f32_e32 v71, 0x3e38aa3b, v93
	v_max3_f32 v12, v12, v90, v91
	v_add_f32_e32 v92, v53, v69
	v_add_f32_e32 v93, v55, v71
	v_max3_f32 v64, v12, v92, v93
	ds_read2_b32 v[12:13], v63 offset0:100 offset1:131
	ds_read2_b32 v[14:15], v79 offset0:100 offset1:131
	v_fmac_f32_e32 v73, 0x3e38aa3b, v94
	v_fmac_f32_e32 v75, 0x3e38aa3b, v95
	v_add_f32_e32 v94, v57, v73
	v_add_f32_e32 v95, v59, v75
	s_waitcnt lgkmcnt(1)
	v_fmamk_f32 v12, v96, 0x3e38aa3b, v12
	v_max3_f32 v68, v64, v94, v95
	v_add_f32_e32 v96, v45, v12
	ds_read2_b32 v[64:65], v81 offset0:100 offset1:131
	s_waitcnt lgkmcnt(1)
	v_fmamk_f32 v12, v97, 0x3e38aa3b, v14
	v_add_f32_e32 v97, v47, v12
	ds_read2_b32 v[66:67], v106 offset0:100 offset1:131
	v_max3_f32 v12, v68, v96, v97
	ds_read2_b32 v[68:69], v83 offset0:100 offset1:131
	ds_read2_b32 v[70:71], v111 offset0:100 offset1:131
	ds_read2_b32 v[72:73], v85 offset0:100 offset1:131
	s_waitcnt lgkmcnt(4)
	v_fmamk_f32 v14, v98, 0x3e38aa3b, v64
	ds_read2_b32 v[74:75], v115 offset0:100 offset1:131
	v_add_f32_e32 v64, v49, v14
	s_waitcnt lgkmcnt(4)
	v_fmamk_f32 v14, v99, 0x3e38aa3b, v66
	v_add_f32_e32 v66, v51, v14
	s_waitcnt lgkmcnt(3)
	v_fmamk_f32 v14, v100, 0x3e38aa3b, v68
	v_add_f32_e32 v68, v53, v14
	s_waitcnt lgkmcnt(2)
	v_fmamk_f32 v14, v101, 0x3e38aa3b, v70
	v_add_f32_e32 v70, v55, v14
	s_waitcnt lgkmcnt(1)
	v_fmamk_f32 v14, v102, 0x3e38aa3b, v72
	v_max3_f32 v12, v12, v64, v66
	v_add_f32_e32 v72, v57, v14
	s_waitcnt lgkmcnt(0)
	v_fmamk_f32 v14, v103, 0x3e38aa3b, v74
	v_max3_f32 v12, v12, v68, v70
	v_add_f32_e32 v74, v59, v14
	v_fmac_f32_e32 v13, 0x3e38aa3b, v24
	v_fmac_f32_e32 v15, 0x3e38aa3b, v25
	v_max3_f32 v12, v12, v72, v74
	v_add_f32_e32 v98, v45, v13
	v_add_f32_e32 v99, v47, v15
	v_fmac_f32_e32 v65, 0x3e38aa3b, v26
	v_fmac_f32_e32 v67, 0x3e38aa3b, v27
	v_max3_f32 v12, v12, v98, v99
	v_add_f32_e32 v26, v49, v65
	v_add_f32_e32 v27, v51, v67
	v_fmac_f32_e32 v69, 0x3e38aa3b, v20
	v_fmac_f32_e32 v71, 0x3e38aa3b, v21
	v_max3_f32 v12, v12, v26, v27
	v_add_f32_e32 v65, v53, v69
	v_add_f32_e32 v67, v55, v71
	v_max3_f32 v20, v12, v65, v67
	ds_read2_b32 v[12:13], v63 offset0:162 offset1:193
	ds_read2_b32 v[14:15], v79 offset0:162 offset1:193
	v_fmac_f32_e32 v73, 0x3e38aa3b, v22
	v_fmac_f32_e32 v75, 0x3e38aa3b, v23
	v_add_f32_e32 v69, v57, v73
	v_add_f32_e32 v63, v59, v75
	v_max3_f32 v22, v20, v69, v63
	ds_read2_b32 v[20:21], v81 offset0:162 offset1:193
	s_waitcnt lgkmcnt(2)
	v_fmamk_f32 v12, v16, 0x3e38aa3b, v12
	s_waitcnt lgkmcnt(1)
	v_fmamk_f32 v14, v17, 0x3e38aa3b, v14
	ds_read2_b32 v[16:17], v106 offset0:162 offset1:193
	v_add_f32_e32 v12, v45, v12
	v_add_f32_e32 v71, v47, v14
	v_max3_f32 v14, v22, v12, v71
	s_waitcnt lgkmcnt(1)
	v_fmamk_f32 v18, v18, 0x3e38aa3b, v20
	ds_read2_b32 v[22:23], v83 offset0:162 offset1:193
	v_add_f32_e32 v73, v49, v18
	s_waitcnt lgkmcnt(1)
	v_fmamk_f32 v16, v19, 0x3e38aa3b, v16
	ds_read2_b32 v[18:19], v111 offset0:162 offset1:193
	v_add_f32_e32 v75, v51, v16
	s_waitcnt lgkmcnt(1)
	v_fmamk_f32 v8, v8, 0x3e38aa3b, v22
	v_add_f32_e32 v79, v53, v8
	ds_read2_b32 v[24:25], v85 offset0:162 offset1:193
	s_waitcnt lgkmcnt(1)
; #define LAS __attribute__((address_space(3)))
; __device__ __forceinline__ unsigned cvt_pk_bf16(float lo, float hi) { unsigned r; asm volatile("v_cvt_pk_bf16_f32 %0, %1, %2" : "=v"(r) : "v"(lo), "v"(hi)); return r; }
; __device__ __forceinline__ void attn_phase(const Params& p, LAS unsigned char* lds) {
;     ...
;           for (int j = 0; j < 9; ++j) { *(LAS u32x4*)(Ks + j * 8192 + dstk) = kv[j]; *(LAS u32x4*)(Vs + j * 8192 + dstv) = vv[j]; } }
;     ...
;         mx = fmaxf(mx, __shfl_xor(mx, 16)); mx = fmaxf(mx, __shfl_xor(mx, 32));
;         float sum = 0.f;
; #pragma unroll
;         for (int i = 0; i < 8; ++i)
; #pragma unroll
;             for (int t = 0; t < 2; ++t)
; #pragma unroll
;                 for (int j = 0; j < 4; ++j) { const float e = __builtin_amdgcn_exp2f(s[i][t][j] - mx); s[i][t][j] = e; sum += e; }
;         sum += __shfl_xor(sum, 16); sum += __shfl_xor(sum, 32);
;         const float inv = 1.0f / sum;
;         f32x4 o[4];
; #pragma unroll
;         for (int nb = 0; nb < 4; ++nb) o[nb] = (f32x4){0.f, 0.f, 0.f, 0.f};
;         const int vc = (kc0 >> 3) + fq;
; #pragma unroll
;         for (int i = 0; i < 8; ++i) {
;             u32x4 pw; pw.x = cvt_pk_bf16(s[i][0][0], s[i][0][1]); pw.y = cvt_pk_bf16(s[i][0][2], s[i][0][3]); pw.z = cvt_pk_bf16(s[i][1][0], s[i][1][1]); pw.w = cvt_pk_bf16(s[i][1][2], s[i][1][3]);
	v_fmamk_f32 v16, v9, 0x3e38aa3b, v18
	ds_read2_b32 v[8:9], v115 offset0:162 offset1:193
	v_max3_f32 v14, v14, v73, v75
	v_add_f32_e32 v81, v55, v16
	s_waitcnt lgkmcnt(1)
	v_fmamk_f32 v10, v10, 0x3e38aa3b, v24
	v_max3_f32 v14, v14, v79, v81
	s_waitcnt lgkmcnt(0)
	v_fmamk_f32 v8, v11, 0x3e38aa3b, v8
	v_add_f32_e32 v83, v57, v10
	v_add_f32_e32 v85, v59, v8
	v_fmac_f32_e32 v13, 0x3e38aa3b, v0
	v_fmac_f32_e32 v15, 0x3e38aa3b, v1
	v_max3_f32 v8, v14, v83, v85
	v_add_f32_e32 v100, v45, v13
	v_add_f32_e32 v101, v47, v15
	v_fmac_f32_e32 v21, 0x3e38aa3b, v2
	v_fmac_f32_e32 v17, 0x3e38aa3b, v3
	v_and_b32_e32 v2, 64, v62
	v_max3_f32 v0, v8, v100, v101
	v_add_f32_e32 v102, v49, v21
	v_add_f32_e32 v103, v51, v17
	v_fmac_f32_e32 v23, 0x3e38aa3b, v4
	v_fmac_f32_e32 v19, 0x3e38aa3b, v5
	v_xor_b32_e32 v1, 16, v62
	v_add_u32_e32 v2, 64, v2
	v_max3_f32 v0, v0, v102, v103
	v_add_f32_e32 v106, v53, v23
	v_add_f32_e32 v111, v55, v19
	v_fmac_f32_e32 v25, 0x3e38aa3b, v6
	v_fmac_f32_e32 v9, 0x3e38aa3b, v7
	v_cmp_lt_i32_e32 vcc, v1, v2
	v_max3_f32 v0, v0, v106, v111
	v_add_f32_e32 v115, v57, v25
	v_add_f32_e32 v119, v59, v9
	v_cndmask_b32_e32 v1, v62, v1, vcc
	v_max3_f32 v0, v0, v115, v119
	v_lshlrev_b32_e32 v16, 2, v1
	ds_bpermute_b32 v1, v16, v0
	s_waitcnt lgkmcnt(0)
	v_max_f32_e32 v1, v1, v1
	v_max_f32_e32 v0, v0, v1
	v_xor_b32_e32 v1, 32, v62
	v_cmp_lt_i32_e32 vcc, v1, v2
	s_nop 1
	v_cndmask_b32_e32 v1, v62, v1, vcc
	v_lshlrev_b32_e32 v17, 2, v1
	ds_bpermute_b32 v1, v17, v0
	s_waitcnt lgkmcnt(0)
	v_max_f32_e32 v1, v1, v1
	v_max_f32_e32 v124, v0, v1
	v_sub_f32_e32 v0, v104, v124
	v_exp_f32_e32 v0, v0
	v_sub_f32_e32 v1, v112, v124
	v_exp_f32_e32 v1, v1
	v_sub_f32_e32 v2, v113, v124
	v_exp_f32_e32 v2, v2
	v_sub_f32_e32 v3, v116, v124
	v_exp_f32_e32 v3, v3
	v_sub_f32_e32 v5, v117, v124
	v_add_f32_e32 v4, 0, v0
	v_exp_f32_e32 v5, v5
	v_sub_f32_e32 v6, v120, v124
	v_add_f32_e32 v4, v1, v4
	v_exp_f32_e32 v6, v6
	v_sub_f32_e32 v7, v121, v124
	v_add_f32_e32 v4, v2, v4
	v_exp_f32_e32 v7, v7
	v_sub_f32_e32 v8, v108, v124
	v_add_f32_e32 v4, v3, v4
	v_exp_f32_e32 v8, v8
	v_sub_f32_e32 v9, v105, v124
	v_add_f32_e32 v4, v5, v4
	v_exp_f32_e32 v22, v9
	v_sub_f32_e32 v9, v107, v124
	v_add_f32_e32 v4, v6, v4
	v_exp_f32_e32 v23, v9
	v_sub_f32_e32 v9, v122, v124
	v_add_f32_e32 v4, v7, v4
	v_exp_f32_e32 v24, v9
	v_sub_f32_e32 v9, v123, v124
	v_add_f32_e32 v4, v8, v4
	v_exp_f32_e32 v25, v9
	v_sub_f32_e32 v9, v76, v124
	v_add_f32_e32 v4, v22, v4
	v_exp_f32_e32 v76, v9
	v_sub_f32_e32 v9, v77, v124
	v_add_f32_e32 v4, v23, v4
	v_exp_f32_e32 v77, v9
	v_sub_f32_e32 v9, v78, v124
	v_add_f32_e32 v4, v24, v4
	v_exp_f32_e32 v78, v9
	v_sub_f32_e32 v9, v109, v124
	v_add_f32_e32 v4, v25, v4
	v_exp_f32_e32 v104, v9
	v_sub_f32_e32 v9, v80, v124
	v_add_f32_e32 v4, v76, v4
	v_exp_f32_e32 v80, v9
	v_sub_f32_e32 v9, v110, v124
	v_add_f32_e32 v4, v77, v4
	v_exp_f32_e32 v105, v9
	v_sub_f32_e32 v9, v82, v124
	v_add_f32_e32 v4, v78, v4
	v_exp_f32_e32 v82, v9
	v_sub_f32_e32 v9, v114, v124
	v_add_f32_e32 v4, v104, v4
	v_exp_f32_e32 v107, v9
	v_sub_f32_e32 v9, v84, v124
	v_add_f32_e32 v4, v80, v4
	v_exp_f32_e32 v84, v9
	v_sub_f32_e32 v9, v118, v124
	v_add_f32_e32 v4, v105, v4
	v_exp_f32_e32 v108, v9
	v_sub_f32_e32 v9, v86, v124
	v_add_f32_e32 v4, v82, v4
	v_exp_f32_e32 v86, v9
	v_sub_f32_e32 v9, v87, v124
	v_add_f32_e32 v4, v107, v4
	v_exp_f32_e32 v87, v9
	v_sub_f32_e32 v9, v88, v124
	v_add_f32_e32 v4, v84, v4
	v_exp_f32_e32 v88, v9
	v_sub_f32_e32 v9, v89, v124
	v_add_f32_e32 v4, v108, v4
	v_exp_f32_e32 v89, v9
	v_sub_f32_e32 v9, v90, v124
	v_add_f32_e32 v4, v86, v4
	v_exp_f32_e32 v90, v9
	v_sub_f32_e32 v9, v91, v124
	v_add_f32_e32 v4, v87, v4
	v_exp_f32_e32 v91, v9
	v_sub_f32_e32 v9, v92, v124
	v_add_f32_e32 v4, v88, v4
	v_exp_f32_e32 v92, v9
	v_sub_f32_e32 v9, v93, v124
	v_add_f32_e32 v4, v89, v4
	v_exp_f32_e32 v93, v9
	v_sub_f32_e32 v9, v94, v124
	v_add_f32_e32 v4, v90, v4
	v_exp_f32_e32 v94, v9
	v_sub_f32_e32 v9, v95, v124
	v_add_f32_e32 v4, v91, v4
	v_exp_f32_e32 v95, v9
	v_sub_f32_e32 v9, v96, v124
	v_add_f32_e32 v4, v92, v4
	v_exp_f32_e32 v96, v9
	v_sub_f32_e32 v9, v97, v124
	v_add_f32_e32 v4, v93, v4
	v_exp_f32_e32 v97, v9
	v_sub_f32_e32 v9, v64, v124
	v_add_f32_e32 v4, v94, v4
	v_exp_f32_e32 v109, v9
	v_sub_f32_e32 v9, v66, v124
	v_add_f32_e32 v4, v95, v4
	v_exp_f32_e32 v110, v9
	v_sub_f32_e32 v9, v68, v124
	v_add_f32_e32 v4, v96, v4
	v_exp_f32_e32 v112, v9
	v_sub_f32_e32 v9, v70, v124
	v_add_f32_e32 v4, v97, v4
	v_exp_f32_e32 v113, v9
	v_sub_f32_e32 v9, v72, v124
	v_add_f32_e32 v4, v109, v4
	v_exp_f32_e32 v114, v9
	v_sub_f32_e32 v9, v74, v124
	v_add_f32_e32 v4, v110, v4
	v_exp_f32_e32 v116, v9
	v_sub_f32_e32 v9, v98, v124
	v_add_f32_e32 v4, v112, v4
	v_exp_f32_e32 v98, v9
	v_sub_f32_e32 v9, v99, v124
	v_add_f32_e32 v4, v113, v4
	v_exp_f32_e32 v99, v9
	v_sub_f32_e32 v9, v26, v124
	v_add_f32_e32 v4, v114, v4
	v_exp_f32_e32 v26, v9
	v_sub_f32_e32 v9, v27, v124
	v_add_f32_e32 v4, v116, v4
	v_exp_f32_e32 v27, v9
	v_add_f32_e32 v4, v98, v4
	v_add_f32_e32 v4, v99, v4
	v_add_f32_e32 v4, v26, v4
	v_add_f32_e32 v13, v27, v4
	v_sub_f32_e32 v4, v65, v124
	v_exp_f32_e32 v117, v4
	v_sub_f32_e32 v4, v67, v124
	v_exp_f32_e32 v118, v4
	v_sub_f32_e32 v9, v69, v124
	v_cvt_pk_bf16_f32 v0, v0, v1
	v_cvt_pk_bf16_f32 v1, v2, v3
	v_cvt_pk_bf16_f32 v2, v5, v6
	v_cvt_pk_bf16_f32 v3, v7, v8
	v_exp_f32_e32 v121, v9
	v_sub_f32_e32 v8, v63, v124
	v_exp_f32_e32 v63, v8
	v_add_f32_e32 v13, v117, v13
	v_add_f32_e32 v13, v118, v13
	v_add_u32_e32 v120, s16, v41
	v_add_f32_e32 v13, v121, v13
	v_sub_f32_e32 v18, v12, v124
	s_waitcnt vmcnt(8)
	ds_write_b128 v38, v[176:179]
	s_waitcnt vmcnt(7)
	ds_write_b128 v38, v[180:183] offset:8192
	s_waitcnt vmcnt(6)
	ds_write_b128 v38, v[184:187] offset:16384
	s_waitcnt vmcnt(5)
	ds_write_b128 v38, v[188:191] offset:24576
	s_waitcnt vmcnt(4)
	ds_write_b128 v38, v[192:195] offset:32768
	s_waitcnt vmcnt(3)
	ds_write_b128 v38, v[196:199] offset:40960
	s_waitcnt vmcnt(2)
	ds_write_b128 v38, v[200:203] offset:49152
	s_waitcnt vmcnt(1)
	ds_write_b128 v38, v[204:207] offset:57344
	s_waitcnt vmcnt(0)
	ds_write_b128 v44, v[208:211]
	s_waitcnt lgkmcnt(0)
	s_barrier
	s_and_saveexec_b64 s[98:99], s[58:59]
	s_cbranch_execz .Lattn_pf_b
	v_mov_b32_e32 v243, 1
	global_atomic_add v242, v31, v243, s[14:15] sc0
; #define LAS __attribute__((address_space(3)))
; __device__ __forceinline__ unsigned cvt_pk_bf16(float lo, float hi) { unsigned r; asm volatile("v_cvt_pk_bf16_f32 %0, %1, %2" : "=v"(r) : "v"(lo), "v"(hi)); return r; }
; __device__ __forceinline__ void attn_phase(const Params& p, LAS unsigned char* lds) {
;     ...
;         const int vc = (kc0 >> 3) + fq;
; #pragma unroll
;         for (int i = 0; i < 8; ++i) {
;             u32x4 pw; pw.x = cvt_pk_bf16(s[i][0][0], s[i][0][1]); pw.y = cvt_pk_bf16(s[i][0][2], s[i][0][3]); pw.z = cvt_pk_bf16(s[i][1][0], s[i][1][1]); pw.w = cvt_pk_bf16(s[i][1][2], s[i][1][3]);
;             const bf16x8 pf = __builtin_bit_cast(bf16x8, pw);
; #pragma unroll
;             for (int nb = 0; nb < 4; ++nb) { const int d = nb * 16 + fr; const bf16x8 va = *(const LAS bf16x8*)(Vs + (j0 + i) * 8192 + d * 128 + ((vc ^ ((d >> 1) & 7)) << 4));
;                 o[nb] = __builtin_amdgcn_mfma_f32_16x16x32_bf16(va, pf, o[nb], 0, 0, 0); } }
.Lattn_pf_b:
	s_or_b64 exec, exec, s[98:99]
	ds_read_b128 v[4:7], v120
	ds_read_b128 v[8:11], v120 offset:2048
	v_add_f32_e32 v72, v63, v13
	ds_read_b128 v[12:15], v120 offset:4096
	v_exp_f32_e32 v122, v18
	ds_read_b128 v[18:21], v120 offset:6144
	v_sub_f32_e32 v68, v71, v124
	v_cvt_pk_bf16_f32 v22, v22, v23
	v_cvt_pk_bf16_f32 v23, v24, v25
	v_cvt_pk_bf16_f32 v24, v76, v77
	v_exp_f32_e32 v76, v68
	v_cvt_pk_bf16_f32 v25, v78, v104
	ds_read_b128 v[64:67], v120 offset:8192
	ds_read_b128 v[68:71], v120 offset:10240
	s_waitcnt lgkmcnt(5)
	v_mfma_f32_16x16x32_bf16 v[4:7], v[4:7], v[0:3], 0
	v_sub_f32_e32 v104, v75, v124
	s_lshl_b32 s16, s43, 11
	s_add_i32 s44, s44, s16
	s_waitcnt lgkmcnt(4)
	v_mfma_f32_16x16x32_bf16 v[8:11], v[8:11], v[0:3], 0
	s_waitcnt lgkmcnt(3)
	v_mfma_f32_16x16x32_bf16 v[12:15], v[12:15], v[0:3], 0
	s_waitcnt lgkmcnt(2)
	v_mfma_f32_16x16x32_bf16 v[0:3], v[18:21], v[0:3], 0
	v_add_f32_e32 v18, v122, v72
	v_add_f32_e32 v77, v76, v18
	v_sub_f32_e32 v18, v73, v124
	v_exp_f32_e32 v78, v18
	ds_read_b128 v[18:21], v120 offset:12288
	s_waitcnt lgkmcnt(2)
	v_mfma_f32_16x16x32_bf16 v[4:7], v[64:67], v[22:25], v[4:7]
	ds_read_b128 v[64:67], v120 offset:14336
	v_add_f32_e32 v77, v78, v77
	s_waitcnt lgkmcnt(2)
	v_mfma_f32_16x16x32_bf16 v[8:11], v[68:71], v[22:25], v[8:11]
	v_cvt_pk_bf16_f32 v68, v80, v105
	v_cvt_pk_bf16_f32 v69, v82, v107
	v_cvt_pk_bf16_f32 v70, v84, v108
	v_cvt_pk_bf16_f32 v71, v86, v87
	ds_read_b128 v[72:75], v120 offset:16384
	s_waitcnt lgkmcnt(2)
	v_mfma_f32_16x16x32_bf16 v[12:15], v[18:21], v[22:25], v[12:15]
	ds_read_b128 v[18:21], v120 offset:18432
	v_exp_f32_e32 v80, v104
	v_sub_f32_e32 v86, v102, v124
	s_waitcnt lgkmcnt(2)
	v_mfma_f32_16x16x32_bf16 v[0:3], v[64:67], v[22:25], v[0:3]
	v_sub_f32_e32 v22, v79, v124
	v_exp_f32_e32 v79, v22
	ds_read_b128 v[22:25], v120 offset:20480
	s_waitcnt lgkmcnt(1)
	v_mfma_f32_16x16x32_bf16 v[8:11], v[18:21], v[68:71], v[8:11]
	ds_read_b128 v[18:21], v120 offset:22528
	v_sub_f32_e32 v64, v81, v124
	v_exp_f32_e32 v81, v64
	s_waitcnt lgkmcnt(1)
	v_mfma_f32_16x16x32_bf16 v[12:15], v[22:25], v[68:71], v[12:15]
	v_sub_f32_e32 v22, v83, v124
	v_exp_f32_e32 v82, v22
	v_add_f32_e32 v77, v80, v77
	s_waitcnt lgkmcnt(0)
	v_mfma_f32_16x16x32_bf16 v[0:3], v[18:21], v[68:71], v[0:3]
	v_add_f32_e32 v18, v79, v77
	v_cvt_pk_bf16_f32 v64, v88, v89
	v_cvt_pk_bf16_f32 v65, v90, v91
	v_mfma_f32_16x16x32_bf16 v[4:7], v[72:75], v[68:71], v[4:7]
	v_cvt_pk_bf16_f32 v66, v92, v93
	v_cvt_pk_bf16_f32 v67, v94, v95
	ds_read_b128 v[72:75], v120 offset:24576
	ds_read_b128 v[22:25], v120 offset:26624
	v_add_f32_e32 v18, v81, v18
	v_add_f32_e32 v77, v82, v18
	ds_read_b128 v[18:21], v120 offset:28672
	s_waitcnt lgkmcnt(1)
	v_mfma_f32_16x16x32_bf16 v[8:11], v[22:25], v[64:67], v[8:11]
	ds_read_b128 v[22:25], v120 offset:30720
	v_sub_f32_e32 v68, v85, v124
	v_exp_f32_e32 v83, v68
	s_waitcnt lgkmcnt(1)
	v_mfma_f32_16x16x32_bf16 v[12:15], v[18:21], v[64:67], v[12:15]
	v_sub_f32_e32 v18, v100, v124
	v_cvt_pk_bf16_f32 v68, v96, v97
	v_cvt_pk_bf16_f32 v69, v109, v110
	v_mfma_f32_16x16x32_bf16 v[4:7], v[72:75], v[64:67], v[4:7]
	v_cvt_pk_bf16_f32 v70, v112, v113
	v_cvt_pk_bf16_f32 v71, v114, v116
	ds_read_b128 v[72:75], v120 offset:32768
	v_exp_f32_e32 v84, v18
	ds_read_b128 v[18:21], v120 offset:34816
	s_waitcnt lgkmcnt(2)
	v_mfma_f32_16x16x32_bf16 v[0:3], v[22:25], v[64:67], v[0:3]
	v_add_f32_e32 v22, v83, v77
	v_add_f32_e32 v77, v84, v22
	v_sub_f32_e32 v22, v101, v124
	v_exp_f32_e32 v85, v22
	ds_read_b128 v[22:25], v120 offset:36864
	s_waitcnt lgkmcnt(1)
	v_mfma_f32_16x16x32_bf16 v[8:11], v[18:21], v[68:71], v[8:11]
	ds_read_b128 v[18:21], v120 offset:38912
	v_cvt_pk_bf16_f32 v64, v98, v99
	v_cvt_pk_bf16_f32 v65, v26, v27
	v_exp_f32_e32 v26, v86
	v_sub_f32_e32 v27, v103, v124
	v_exp_f32_e32 v27, v27
	s_waitcnt lgkmcnt(0)
	v_mfma_f32_16x16x32_bf16 v[0:3], v[18:21], v[68:71], v[0:3]
	v_add_f32_e32 v18, v85, v77
	v_add_f32_e32 v18, v26, v18
	v_cvt_pk_bf16_f32 v66, v117, v118
	v_mfma_f32_16x16x32_bf16 v[4:7], v[72:75], v[68:71], v[4:7]
	v_cvt_pk_bf16_f32 v67, v121, v63
	ds_read_b128 v[72:75], v120 offset:40960
	v_add_f32_e32 v63, v27, v18
	v_mfma_f32_16x16x32_bf16 v[12:15], v[22:25], v[68:71], v[12:15]
	ds_read_b128 v[22:25], v120 offset:43008
	ds_read_b128 v[18:21], v120 offset:45056
	v_sub_f32_e32 v77, v106, v124
	s_waitcnt lgkmcnt(2)
; #define LAS __attribute__((address_space(3)))
; __device__ __forceinline__ unsigned cvt_pk_bf16(float lo, float hi) { unsigned r; asm volatile("v_cvt_pk_bf16_f32 %0, %1, %2" : "=v"(r) : "v"(lo), "v"(hi)); return r; }
; __device__ __forceinline__ void attn_phase(const Params& p, LAS unsigned char* lds) {
;     ...
;         sum += __shfl_xor(sum, 16); sum += __shfl_xor(sum, 32);
;         const float inv = 1.0f / sum;
;         f32x4 o[4];
; #pragma unroll
;         for (int nb = 0; nb < 4; ++nb) o[nb] = (f32x4){0.f, 0.f, 0.f, 0.f};
;         const int vc = (kc0 >> 3) + fq;
; #pragma unroll
;         for (int i = 0; i < 8; ++i) {
;             u32x4 pw; pw.x = cvt_pk_bf16(s[i][0][0], s[i][0][1]); pw.y = cvt_pk_bf16(s[i][0][2], s[i][0][3]); pw.z = cvt_pk_bf16(s[i][1][0], s[i][1][1]); pw.w = cvt_pk_bf16(s[i][1][2], s[i][1][3]);
;             const bf16x8 pf = __builtin_bit_cast(bf16x8, pw);
; #pragma unroll
;             for (int nb = 0; nb < 4; ++nb) { const int d = nb * 16 + fr; const bf16x8 va = *(const LAS bf16x8*)(Vs + (j0 + i) * 8192 + d * 128 + ((vc ^ ((d >> 1) & 7)) << 4));
;                 o[nb] = __builtin_amdgcn_mfma_f32_16x16x32_bf16(va, pf, o[nb], 0, 0, 0); } }
;         float q2 = 0.f;
; #pragma unroll
;         for (int nb = 0; nb < 4; ++nb) { o[nb] = o[nb] * inv; q2 += (o[nb][0] * o[nb][0] + o[nb][1] * o[nb][1]) + (o[nb][2] * o[nb][2] + o[nb][3] * o[nb][3]); }
;         q2 += __shfl_xor(q2, 16); q2 += __shfl_xor(q2, 32);
;         if (fq == 0) SSQNA[(size_t)tq * 8 + h] = q2;
	v_mfma_f32_16x16x32_bf16 v[4:7], v[72:75], v[64:67], v[4:7]
	s_waitcnt lgkmcnt(1)
	v_mfma_f32_16x16x32_bf16 v[8:11], v[22:25], v[64:67], v[8:11]
	ds_read_b128 v[22:25], v120 offset:47104
	v_cvt_pk_bf16_f32 v68, v122, v76
	v_cvt_pk_bf16_f32 v69, v78, v80
	v_cvt_pk_bf16_f32 v70, v79, v81
	v_cvt_pk_bf16_f32 v71, v82, v83
	ds_read_b128 v[72:75], v120 offset:49152
	s_waitcnt lgkmcnt(2)
	v_mfma_f32_16x16x32_bf16 v[12:15], v[18:21], v[64:67], v[12:15]
	ds_read_b128 v[18:21], v120 offset:51200
	v_exp_f32_e32 v76, v77
	v_sub_f32_e32 v77, v111, v124
	s_waitcnt lgkmcnt(2)
	v_mfma_f32_16x16x32_bf16 v[0:3], v[22:25], v[64:67], v[0:3]
	ds_read_b128 v[22:25], v120 offset:53248
	v_exp_f32_e32 v64, v77
	v_sub_f32_e32 v65, v115, v124
	s_waitcnt lgkmcnt(1)
	v_mfma_f32_16x16x32_bf16 v[8:11], v[18:21], v[68:71], v[8:11]
	v_sub_f32_e32 v18, v119, v124
	v_add_f32_e32 v63, v76, v63
	v_add_f32_e32 v63, v64, v63
	v_mfma_f32_16x16x32_bf16 v[4:7], v[72:75], v[68:71], v[4:7]
	v_exp_f32_e32 v73, v18
	ds_read_b128 v[18:21], v120 offset:55296
	v_exp_f32_e32 v72, v65
	s_waitcnt lgkmcnt(1)
	v_mfma_f32_16x16x32_bf16 v[12:15], v[22:25], v[68:71], v[12:15]
	v_cvt_pk_bf16_f32 v22, v84, v85
	v_cvt_pk_bf16_f32 v23, v26, v27
	v_add_f32_e32 v26, v72, v63
	v_cvt_pk_bf16_f32 v24, v76, v64
	v_cvt_pk_bf16_f32 v25, v72, v73
	ds_read_b128 v[64:67], v120 offset:57344
	v_add_f32_e32 v26, v73, v26
	s_waitcnt lgkmcnt(1)
	v_mfma_f32_16x16x32_bf16 v[0:3], v[18:21], v[68:71], v[0:3]
	ds_read_b128 v[18:21], v120 offset:59392
	ds_bpermute_b32 v27, v16, v26
	ds_read_b128 v[68:71], v120 offset:61440
	s_waitcnt lgkmcnt(2)
	v_mfma_f32_16x16x32_bf16 v[18:21], v[18:21], v[22:25], v[8:11]
	s_waitcnt lgkmcnt(1)
	v_add_f32_e32 v26, v26, v27
	ds_bpermute_b32 v27, v17, v26
	ds_read_b128 v[8:11], v120 offset:63488
	v_mfma_f32_16x16x32_bf16 v[4:7], v[64:67], v[22:25], v[4:7]
	s_waitcnt lgkmcnt(1)
	v_add_f32_e32 v26, v26, v27
	v_div_scale_f32 v27, s[20:21], v26, v26, 1.0
	v_rcp_f32_e32 v63, v27
	v_mfma_f32_16x16x32_bf16 v[12:15], v[68:71], v[22:25], v[12:15]
	s_waitcnt lgkmcnt(0)
	v_mfma_f32_16x16x32_bf16 v[22:25], v[8:11], v[22:25], v[0:3]
	s_nop 2
	v_fma_f32 v0, -v27, v63, 1.0
	v_fmac_f32_e32 v63, v0, v63
	v_div_scale_f32 v0, vcc, 1.0, v26, 1.0
	v_mul_f32_e32 v1, v0, v63
	v_fma_f32 v2, -v27, v1, v0
	v_fmac_f32_e32 v1, v2, v63
	v_fma_f32 v0, -v27, v1, v0
	v_div_fmas_f32 v0, v0, v63, v1
	v_div_fixup_f32 v26, v0, v26, 1.0
	v_pk_mul_f32 v[2:3], v[26:27], v[6:7] op_sel_hi:[0,1]
	v_pk_mul_f32 v[10:11], v[26:27], v[4:5] op_sel_hi:[0,1]
	v_mul_f32_e32 v0, v11, v11
	v_mul_f32_e32 v1, v3, v3
	v_fmac_f32_e32 v0, v10, v10
	v_fmac_f32_e32 v1, v2, v2
	v_add_f32_e32 v4, v0, v1
	v_pk_mul_f32 v[0:1], v[26:27], v[20:21] op_sel_hi:[0,1]
	v_pk_mul_f32 v[6:7], v[26:27], v[18:19] op_sel_hi:[0,1]
	v_mul_f32_e32 v5, v7, v7
	v_mul_f32_e32 v8, v1, v1
	v_fmac_f32_e32 v5, v6, v6
	v_fmac_f32_e32 v8, v0, v0
	v_add_f32_e32 v5, v5, v8
	v_add_f32_e32 v8, v4, v5
	v_pk_mul_f32 v[4:5], v[26:27], v[14:15] op_sel_hi:[0,1]
	v_pk_mul_f32 v[12:13], v[26:27], v[12:13] op_sel_hi:[0,1]
	v_mul_f32_e32 v9, v13, v13
	v_mul_f32_e32 v14, v5, v5
	v_fmac_f32_e32 v9, v12, v12
	v_fmac_f32_e32 v14, v4, v4
	v_add_f32_e32 v9, v9, v14
	v_add_f32_e32 v18, v8, v9
	v_pk_mul_f32 v[8:9], v[26:27], v[24:25] op_sel_hi:[0,1]
	v_pk_mul_f32 v[14:15], v[26:27], v[22:23] op_sel_hi:[0,1]
	v_mul_f32_e32 v19, v15, v15
	v_mul_f32_e32 v20, v9, v9
	v_fmac_f32_e32 v19, v14, v14
	v_fmac_f32_e32 v20, v8, v8
	v_add_f32_e32 v19, v19, v20
	v_add_f32_e32 v18, v18, v19
	ds_bpermute_b32 v16, v16, v18
	s_waitcnt lgkmcnt(0)
	v_add_f32_e32 v18, v18, v16
	ds_bpermute_b32 v19, v17, v18
	v_or_b32_e32 v16, s44, v28
	v_ashrrev_i32_e32 v17, 31, v16
	s_and_saveexec_b64 s[20:21], s[4:5]
	s_cbranch_execz .LBB0_336
	s_waitcnt lgkmcnt(0)
	v_add_f32_e32 v20, v18, v19
	v_lshlrev_b64 v[18:19], 5, v[16:17]
	v_lshl_add_u64 v[18:19], s[12:13], 0, v[18:19]
	s_lshl_b32 s16, s42, 2
	v_lshl_add_u64 v[18:19], v[18:19], 0, s[16:17]
	global_store_dword v[18:19], v20, off
	s_branch .LBB0_336
